# speedup vs baseline: 1.0510x; 1.0008x over previous
; __device__ __forceinline__ unsigned pk2(float lo, float hi) { f32x2 v = {lo, hi}; bf16x2_t b = __builtin_convertvector(v, bf16x2_t); return __builtin_bit_cast(unsigned, b); }
; __device__ __forceinline__ float silu_f(float z) { return z * __builtin_amdgcn_rcpf(1.0f + __expf(-z)); }
; __device__ __forceinline__ int launder_v(int x) { asm volatile("" : "+v"(x)); return x; }
; __device__ __forceinline__ int launder_s(int x) { asm volatile("" : "+s"(x)); return x; }
; __device__ __forceinline__ float swap_add(float v) { unsigned a = __builtin_bit_cast(unsigned, v), b = a; asm volatile("s_nop 1\n\tv_permlane32_swap_b32 %0, %1\n\ts_nop 1" : "+v"(a), "+v"(b)); return __builtin_bit_cast(float, a) + __builtin_bit_cast(float, b); }
; template <int MODE>
; __device__ __forceinline__ void attn_unit(LAS unsigned char* lds, const bf16_t* __restrict__ qkvz, bf16_t* __restrict__ A2, const int b, const int hd, const int qb, const AttnX& X, const int tid) {
;     ...
;     const float l_tot = swap_add(l_run);
;     const float inv = 1.0f / l_tot;
;     const int lane_e = launder_v(lane);
;     const size_t trow = (size_t)launder_s(b) * SEQ + launder_s(q0w) + (lane_e & 31);
;     if (MODE != 0) {
;         const int hh_e = lane_e >> 5;
;         u32x2 zz[NDT * 4];
; #pragma unroll
;         for (int d = 0; d < NDT; ++d)
; #pragma unroll
;             for (int i4 = 0; i4 < 4; ++i4) zz[d * 4 + i4] = *(const u32x2*)(qkvz + trow * LD + zcol + 32 * d + 8 * i4 + 4 * hh_e);
; #pragma unroll
;         for (int d = 0; d < NDT; ++d)
; #pragma unroll
;             for (int i4 = 0; i4 < 4; ++i4) { const int dd = 32 * d + 8 * i4 + 4 * hh_e; const u32x2 z2 = zz[d * 4 + i4];
;                 u32x2 w;
;                 w.x = pk2(O[d][4 * i4 + 0] * inv * silu_f(bflo(z2.x)), O[d][4 * i4 + 1] * inv * silu_f(bfhi(z2.x)));
;                 w.y = pk2(O[d][4 * i4 + 2] * inv * silu_f(bflo(z2.y)), O[d][4 * i4 + 3] * inv * silu_f(bfhi(z2.y)));
;                 *(u32x2*)(A2 + trow * DM + hd * C::DV + dd) = w; }
.LBB0_585:
	v_cmp_eq_u32_e64 s[44:45], 0, v212
	s_and_saveexec_b64 s[46:47], s[44:45]
	s_cbranch_execz .Lband_pf_skip
	v_mov_b32_e32 v154, 0x93a0040
	v_mov_b32_e32 v155, 1
	global_atomic_add v154, v154, v155, s[72:73] sc0
.Lband_pf_skip:
	s_or_b64 exec, exec, s[46:47]
	s_nop 1
	v_mov_b32_e32 v40, v146
	v_mov_b32_e32 v36, v125
	s_nop 1
	v_permlane32_swap_b32 v146, v40
	s_nop 1
	s_ashr_i32 s29, s28, 31
	s_lshl_b64 s[0:1], s[28:29], 13
	s_ashr_i32 s12, s39, 31
	s_add_u32 s0, s0, s39
	v_and_b32_e32 v80, 31, v36
	s_addc_u32 s1, s1, s12
	v_lshl_add_u64 v[32:33], s[0:1], 0, v[80:81]
	v_ashrrev_i32_e32 v36, 3, v36
	v_lshlrev_b64 v[34:35], 14, v[32:33]
	v_and_b32_e32 v36, -4, v36
	v_lshl_add_u64 v[34:35], s[84:85], 0, v[34:35]
	v_ashrrev_i32_e32 v37, 31, v36
	v_lshl_add_u64 v[34:35], v[34:35], 0, s[14:15]
	v_lshlrev_b64 v[36:37], 1, v[36:37]
	v_lshl_add_u64 v[34:35], v[34:35], 0, v[36:37]
	v_add_co_u32_e32 v38, vcc, s33, v34
	v_add_f32_e32 v52, v146, v40
	s_nop 0
	v_addc_co_u32_e32 v39, vcc, 0, v35, vcc
	global_load_dwordx2 v[42:43], v[38:39], off
	v_lshl_add_u64 v[34:35], v[34:35], 0, s[26:27]
	global_load_dwordx2 v[44:45], v[34:35], off offset:16
	global_load_dwordx2 v[46:47], v[34:35], off offset:32
	v_div_scale_f32 v53, s[0:1], v52, v52, 1.0
	v_rcp_f32_e32 v54, v53
	v_lshlrev_b64 v[32:33], 12, v[32:33]
	v_lshl_add_u64 v[32:33], s[94:95], 0, v[32:33]
	v_lshl_add_u64 v[32:33], v[32:33], 0, s[14:15]
	v_fma_f32 v38, -v53, v54, 1.0
	v_fmac_f32_e32 v54, v38, v54
	v_lshl_add_u64 v[32:33], v[32:33], 0, v[36:37]
	global_load_dwordx2 v[48:49], v[34:35], off offset:48
	global_load_dwordx2 v[50:51], v[34:35], off offset:64
	global_load_dwordx2 v[40:41], v[34:35], off offset:80
	global_load_dwordx2 v[38:39], v[34:35], off offset:96
	global_load_dwordx2 v[36:37], v[34:35], off offset:112
	v_div_scale_f32 v55, vcc, 1.0, v52, 1.0
	v_mul_f32_e32 v56, v55, v54
	v_fma_f32 v57, -v53, v56, v55
	v_fmac_f32_e32 v56, v57, v54
	v_fma_f32 v34, -v53, v56, v55
	v_div_fmas_f32 v34, v34, v54, v56
	v_div_fixup_f32 v34, v34, v52, 1.0
	v_pk_mul_f32 v[16:17], v[16:17], v[34:35] op_sel_hi:[1,0]
	v_pk_mul_f32 v[18:19], v[18:19], v[34:35] op_sel_hi:[1,0]
	v_pk_mul_f32 v[20:21], v[20:21], v[34:35] op_sel_hi:[1,0]
	v_pk_mul_f32 v[22:23], v[22:23], v[34:35] op_sel_hi:[1,0]
	s_waitcnt vmcnt(7)
	v_lshlrev_b32_e32 v52, 16, v42
	v_and_b32_e32 v53, 0xffff0000, v42
	v_lshlrev_b32_e32 v42, 16, v43
	v_and_b32_e32 v43, 0xffff0000, v43
	s_waitcnt vmcnt(6)
	v_lshlrev_b32_e32 v54, 16, v44
	v_mul_f32_e32 v35, 0xbfb8aa3b, v52
	v_mul_f32_e32 v56, 0xbfb8aa3b, v53
	v_mul_f32_e32 v57, 0xbfb8aa3b, v42
	v_mul_f32_e32 v58, 0xbfb8aa3b, v43
	v_mul_f32_e32 v59, 0xbfb8aa3b, v54
	v_exp_f32_e32 v35, v35
	v_exp_f32_e32 v56, v56
	v_exp_f32_e32 v57, v57
	v_exp_f32_e32 v58, v58
	v_and_b32_e32 v55, 0xffff0000, v44
	v_lshlrev_b32_e32 v44, 16, v45
	v_and_b32_e32 v45, 0xffff0000, v45
	v_exp_f32_e32 v59, v59
	v_mul_f32_e32 v61, 0xbfb8aa3b, v44
	v_mul_f32_e32 v62, 0xbfb8aa3b, v45
	v_mul_f32_e32 v60, 0xbfb8aa3b, v55
	v_exp_f32_e32 v61, v61
	v_exp_f32_e32 v62, v62
	v_exp_f32_e32 v60, v60
	v_add_f32_e32 v35, 1.0, v35
	v_add_f32_e32 v63, 1.0, v56
	v_add_f32_e32 v64, 1.0, v57
	v_add_f32_e32 v65, 1.0, v58
	v_add_f32_e32 v66, 1.0, v59
	v_rcp_f32_e32 v56, v35
	v_rcp_f32_e32 v57, v63
	v_rcp_f32_e32 v58, v64
	v_rcp_f32_e32 v59, v65
	v_add_f32_e32 v68, 1.0, v61
	v_add_f32_e32 v69, 1.0, v62
	v_add_f32_e32 v67, 1.0, v60
	v_rcp_f32_e32 v62, v68
	v_rcp_f32_e32 v63, v69
	v_rcp_f32_e32 v60, v66
	v_rcp_f32_e32 v61, v67
	v_pk_mul_f32 v[52:53], v[56:57], v[52:53]
	v_pk_mul_f32 v[42:43], v[58:59], v[42:43]
	v_pk_mul_f32 v[16:17], v[16:17], v[52:53]
	v_pk_mul_f32 v[18:19], v[18:19], v[42:43]
	v_cvt_pk_bf16_f32 v16, v16, v17
	v_cvt_pk_bf16_f32 v17, v18, v19
	global_store_dwordx2 v[32:33], v[16:17], off
	v_pk_mul_f32 v[16:17], v[62:63], v[44:45]
	v_pk_mul_f32 v[54:55], v[60:61], v[54:55]
	v_pk_mul_f32 v[16:17], v[22:23], v[16:17]
	v_pk_mul_f32 v[20:21], v[20:21], v[54:55]
	v_cvt_pk_bf16_f32 v19, v16, v17
	s_waitcnt vmcnt(6)
	v_lshlrev_b32_e32 v16, 16, v46
	v_cvt_pk_bf16_f32 v18, v20, v21
	v_mul_f32_e32 v17, 0xbfb8aa3b, v16
	global_store_dwordx2 v[32:33], v[18:19], off offset:16
	v_exp_f32_e32 v18, v17
	v_and_b32_e32 v17, 0xffff0000, v46
	v_mul_f32_e32 v19, 0xbfb8aa3b, v17
	v_exp_f32_e32 v19, v19
	v_lshlrev_b32_e32 v22, 16, v47
	v_and_b32_e32 v23, 0xffff0000, v47
	v_add_f32_e32 v18, 1.0, v18
	v_pk_mul_f32 v[20:21], v[24:25], v[34:35] op_sel_hi:[1,0]
	v_add_f32_e32 v19, 1.0, v19
	v_mul_f32_e32 v24, 0xbfb8aa3b, v22
	v_mul_f32_e32 v25, 0xbfb8aa3b, v23
	v_rcp_f32_e32 v18, v18
	v_rcp_f32_e32 v19, v19
	v_exp_f32_e32 v24, v24
	v_exp_f32_e32 v25, v25
	v_pk_mul_f32 v[0:1], v[0:1], v[34:35] op_sel_hi:[1,0]
	v_pk_mul_f32 v[16:17], v[18:19], v[16:17]
	v_add_f32_e32 v18, 1.0, v24
	v_add_f32_e32 v19, 1.0, v25
	v_rcp_f32_e32 v18, v18
	v_rcp_f32_e32 v19, v19
	v_pk_mul_f32 v[16:17], v[20:21], v[16:17]
	v_pk_mul_f32 v[20:21], v[26:27], v[34:35] op_sel_hi:[1,0]
	v_cvt_pk_bf16_f32 v16, v16, v17
	v_pk_mul_f32 v[18:19], v[18:19], v[22:23]
	s_waitcnt vmcnt(6)
; __device__ __forceinline__ unsigned pk2(float lo, float hi) { f32x2 v = {lo, hi}; bf16x2_t b = __builtin_convertvector(v, bf16x2_t); return __builtin_bit_cast(unsigned, b); }
; __device__ __forceinline__ float silu_f(float z) { return z * __builtin_amdgcn_rcpf(1.0f + __expf(-z)); }
; template <int MODE>
; __device__ __forceinline__ void attn_unit(LAS unsigned char* lds, const bf16_t* __restrict__ qkvz, bf16_t* __restrict__ A2, const int b, const int hd, const int qb, const AttnX& X, const int tid) {
;     ...
;         for (int d = 0; d < NDT; ++d)
; #pragma unroll
;             for (int i4 = 0; i4 < 4; ++i4) { const int dd = 32 * d + 8 * i4 + 4 * hh_e; const u32x2 z2 = zz[d * 4 + i4];
;                 u32x2 w;
;                 w.x = pk2(O[d][4 * i4 + 0] * inv * silu_f(bflo(z2.x)), O[d][4 * i4 + 1] * inv * silu_f(bfhi(z2.x)));
;                 w.y = pk2(O[d][4 * i4 + 2] * inv * silu_f(bflo(z2.y)), O[d][4 * i4 + 3] * inv * silu_f(bfhi(z2.y)));
;                 *(u32x2*)(A2 + trow * DM + hd * C::DV + dd) = w; }
;     ...
;     __syncthreads();
	v_lshlrev_b32_e32 v22, 16, v49
	v_pk_mul_f32 v[18:19], v[20:21], v[18:19]
	v_and_b32_e32 v23, 0xffff0000, v49
	v_cvt_pk_bf16_f32 v17, v18, v19
	global_store_dwordx2 v[32:33], v[16:17], off offset:32
	v_lshlrev_b32_e32 v16, 16, v48
	v_mul_f32_e32 v17, 0xbfb8aa3b, v16
	v_exp_f32_e32 v18, v17
	v_and_b32_e32 v17, 0xffff0000, v48
	v_mul_f32_e32 v19, 0xbfb8aa3b, v17
	v_exp_f32_e32 v19, v19
	v_add_f32_e32 v18, 1.0, v18
	v_mul_f32_e32 v24, 0xbfb8aa3b, v22
	v_mul_f32_e32 v25, 0xbfb8aa3b, v23
	v_add_f32_e32 v19, 1.0, v19
	v_rcp_f32_e32 v18, v18
	v_rcp_f32_e32 v19, v19
	v_exp_f32_e32 v24, v24
	v_exp_f32_e32 v25, v25
	v_pk_mul_f32 v[20:21], v[28:29], v[34:35] op_sel_hi:[1,0]
	v_pk_mul_f32 v[16:17], v[18:19], v[16:17]
	v_add_f32_e32 v18, 1.0, v24
	v_add_f32_e32 v19, 1.0, v25
	v_rcp_f32_e32 v18, v18
	v_rcp_f32_e32 v19, v19
	v_pk_mul_f32 v[16:17], v[20:21], v[16:17]
	v_pk_mul_f32 v[20:21], v[30:31], v[34:35] op_sel_hi:[1,0]
	v_cvt_pk_bf16_f32 v16, v16, v17
	v_pk_mul_f32 v[18:19], v[18:19], v[22:23]
	v_pk_mul_f32 v[2:3], v[2:3], v[34:35] op_sel_hi:[1,0]
	v_pk_mul_f32 v[18:19], v[20:21], v[18:19]
	s_waitcnt vmcnt(6)
	v_lshlrev_b32_e32 v20, 16, v51
	v_cvt_pk_bf16_f32 v17, v18, v19
	global_store_dwordx2 v[32:33], v[16:17], off offset:48
	v_lshlrev_b32_e32 v16, 16, v50
	v_mul_f32_e32 v17, 0xbfb8aa3b, v16
	v_exp_f32_e32 v18, v17
	v_and_b32_e32 v17, 0xffff0000, v50
	v_mul_f32_e32 v19, 0xbfb8aa3b, v17
	v_exp_f32_e32 v19, v19
	v_and_b32_e32 v21, 0xffff0000, v51
	v_add_f32_e32 v18, 1.0, v18
	v_mul_f32_e32 v22, 0xbfb8aa3b, v20
	v_add_f32_e32 v19, 1.0, v19
	v_mul_f32_e32 v23, 0xbfb8aa3b, v21
	v_rcp_f32_e32 v18, v18
	v_rcp_f32_e32 v19, v19
	v_exp_f32_e32 v22, v22
	v_exp_f32_e32 v23, v23
	v_pk_mul_f32 v[4:5], v[4:5], v[34:35] op_sel_hi:[1,0]
	v_pk_mul_f32 v[16:17], v[18:19], v[16:17]
	v_add_f32_e32 v18, 1.0, v22
	v_add_f32_e32 v19, 1.0, v23
	v_rcp_f32_e32 v18, v18
	v_rcp_f32_e32 v19, v19
	v_pk_mul_f32 v[0:1], v[0:1], v[16:17]
	v_pk_mul_f32 v[16:17], v[18:19], v[20:21]
	s_nop 0
	v_pk_mul_f32 v[2:3], v[2:3], v[16:17]
	v_cvt_pk_bf16_f32 v0, v0, v1
	v_cvt_pk_bf16_f32 v1, v2, v3
	global_store_dwordx2 v[32:33], v[0:1], off offset:64
	s_waitcnt vmcnt(7)
	v_lshlrev_b32_e32 v0, 16, v40
	v_mul_f32_e32 v1, 0xbfb8aa3b, v0
	v_exp_f32_e32 v2, v1
	v_and_b32_e32 v1, 0xffff0000, v40
	v_mul_f32_e32 v3, 0xbfb8aa3b, v1
	v_exp_f32_e32 v3, v3
	v_lshlrev_b32_e32 v16, 16, v41
	v_and_b32_e32 v17, 0xffff0000, v41
	v_add_f32_e32 v2, 1.0, v2
	v_add_f32_e32 v3, 1.0, v3
	v_mul_f32_e32 v18, 0xbfb8aa3b, v16
	v_mul_f32_e32 v19, 0xbfb8aa3b, v17
	v_rcp_f32_e32 v2, v2
	v_rcp_f32_e32 v3, v3
	v_exp_f32_e32 v18, v18
	v_exp_f32_e32 v19, v19
	v_pk_mul_f32 v[0:1], v[2:3], v[0:1]
	v_add_f32_e32 v2, 1.0, v18
	v_add_f32_e32 v3, 1.0, v19
	v_rcp_f32_e32 v2, v2
	v_rcp_f32_e32 v3, v3
	v_pk_mul_f32 v[0:1], v[4:5], v[0:1]
	v_pk_mul_f32 v[4:5], v[6:7], v[34:35] op_sel_hi:[1,0]
	v_cvt_pk_bf16_f32 v0, v0, v1
	v_pk_mul_f32 v[2:3], v[2:3], v[16:17]
	s_waitcnt vmcnt(6)
	v_lshlrev_b32_e32 v6, 16, v39
	v_pk_mul_f32 v[2:3], v[4:5], v[2:3]
	v_and_b32_e32 v7, 0xffff0000, v39
	v_cvt_pk_bf16_f32 v1, v2, v3
	global_store_dwordx2 v[32:33], v[0:1], off offset:80
	v_lshlrev_b32_e32 v0, 16, v38
	v_mul_f32_e32 v1, 0xbfb8aa3b, v0
	v_exp_f32_e32 v2, v1
	v_and_b32_e32 v1, 0xffff0000, v38
	v_mul_f32_e32 v3, 0xbfb8aa3b, v1
	v_exp_f32_e32 v3, v3
	v_add_f32_e32 v2, 1.0, v2
	v_pk_mul_f32 v[4:5], v[8:9], v[34:35] op_sel_hi:[1,0]
	v_mul_f32_e32 v8, 0xbfb8aa3b, v6
	v_add_f32_e32 v3, 1.0, v3
	v_mul_f32_e32 v9, 0xbfb8aa3b, v7
	v_rcp_f32_e32 v2, v2
	v_rcp_f32_e32 v3, v3
	v_exp_f32_e32 v8, v8
	v_exp_f32_e32 v9, v9
	v_pk_mul_f32 v[0:1], v[2:3], v[0:1]
	v_add_f32_e32 v2, 1.0, v8
	v_add_f32_e32 v3, 1.0, v9
	v_rcp_f32_e32 v2, v2
	v_rcp_f32_e32 v3, v3
	v_pk_mul_f32 v[0:1], v[4:5], v[0:1]
	v_pk_mul_f32 v[4:5], v[10:11], v[34:35] op_sel_hi:[1,0]
	v_cvt_pk_bf16_f32 v0, v0, v1
	v_pk_mul_f32 v[2:3], v[2:3], v[6:7]
	s_waitcnt vmcnt(6)
	v_lshlrev_b32_e32 v6, 16, v37
	v_pk_mul_f32 v[2:3], v[4:5], v[2:3]
	v_and_b32_e32 v7, 0xffff0000, v37
	v_cvt_pk_bf16_f32 v1, v2, v3
	global_store_dwordx2 v[32:33], v[0:1], off offset:96
	v_lshlrev_b32_e32 v0, 16, v36
	v_mul_f32_e32 v1, 0xbfb8aa3b, v0
	v_exp_f32_e32 v2, v1
	v_and_b32_e32 v1, 0xffff0000, v36
	v_mul_f32_e32 v3, 0xbfb8aa3b, v1
	v_exp_f32_e32 v3, v3
	v_add_f32_e32 v2, 1.0, v2
	v_mul_f32_e32 v8, 0xbfb8aa3b, v6
	v_mul_f32_e32 v9, 0xbfb8aa3b, v7
	v_add_f32_e32 v3, 1.0, v3
	v_rcp_f32_e32 v2, v2
	v_rcp_f32_e32 v3, v3
	v_exp_f32_e32 v8, v8
	v_exp_f32_e32 v9, v9
	v_pk_mul_f32 v[4:5], v[12:13], v[34:35] op_sel_hi:[1,0]
	v_pk_mul_f32 v[0:1], v[2:3], v[0:1]
	v_add_f32_e32 v2, 1.0, v8
	v_add_f32_e32 v3, 1.0, v9
	v_rcp_f32_e32 v2, v2
	v_rcp_f32_e32 v3, v3
	v_pk_mul_f32 v[0:1], v[4:5], v[0:1]
	v_pk_mul_f32 v[4:5], v[14:15], v[34:35] op_sel_hi:[1,0]
	v_cvt_pk_bf16_f32 v0, v0, v1
	v_pk_mul_f32 v[2:3], v[2:3], v[6:7]
	s_nop 0
	v_pk_mul_f32 v[2:3], v[4:5], v[2:3]
	s_nop 0
	v_cvt_pk_bf16_f32 v1, v2, v3
	global_store_dwordx2 v[32:33], v[0:1], off offset:112
	s_barrier
	v_cmp_eq_u32_e32 vcc, 0, v212
	s_and_saveexec_b64 s[12:13], vcc
	s_cbranch_execz .Lband_nofetch
	s_waitcnt vmcnt(0)
	v_mov_b32_e32 v1, 0x23ff8
	ds_write_b32 v1, v154

; __device__ __forceinline__ void phase_fox_cumsum(const Params& p, LAS unsigned char* lds) {
;     ...
;     for (int it = bx; it < 256; it += G) { const int bh = it & 63, quarter = it >> 6, b = bh >> 4, h = bh & 15;
;         const bf16_t* Kp = (const bf16_t*)(ws + WS_QKVZ) + 2048 + h * 128; float* KN = (float*)(ws + WS_KN);
; #pragma unroll
;         for (int j = 0; j < 4; ++j) { const int key = quarter * 2048 + j * 512 + tid; const bf16_t* kr = Kp + ((size_t)b * SEQ + key) * 8192; float ss = 0.f;
; #pragma unroll
;             for (int c = 0; c < 16; ++c) { const u32x4 v = *(const u32x4*)(kr + c * 8);
;                 ss += bflo(v.x) * bflo(v.x) + bfhi(v.x) * bfhi(v.x) + bflo(v.y) * bflo(v.y) + bfhi(v.y) * bfhi(v.y) + bflo(v.z) * bflo(v.z) + bfhi(v.z) * bfhi(v.z) + bflo(v.w) * bflo(v.w) + bfhi(v.w) * bfhi(v.w); }
; #pragma unroll
;             for (int o = 1; o < 64; o <<= 1) ss = fmaxf(ss, __shfl_xor(ss, o));
;             if (lane == 0) KN[bh * 128 + quarter * 32 + j * 8 + wid] = ss; } }
.LBB0_921:
	s_and_b32 s4, s17, 0x780
	s_and_b32 s0, s19, 63
	s_ashr_i32 s1, s19, 6
	s_lshl_b32 s4, s4, 1
	s_add_u32 s6, s13, s4
	s_addc_u32 s7, s14, 0
	v_lshrrev_b32_e32 v8, 4, v18
	v_lshl_add_u32 v8, s1, 11, v8
	v_lshl_add_u32 v8, s12, 6, v8
	s_lshl_b32 s4, s19, 9
	s_and_b32 s4, s4, 0x6000
	v_add_u32_e32 v8, s4, v8
	v_mov_b32_e32 v9, 0
	v_lshlrev_b64 v[0:1], 14, v[8:9]
	v_and_b32_e32 v2, 15, v18
	v_lshlrev_b32_e32 v2, 4, v2
	v_mov_b32_e32 v3, 0
	v_lshl_add_u64 v[0:1], v[0:1], 0, v[2:3]
	v_lshl_add_u64 v[10:11], s[6:7], 0, v[0:1]
	s_lshl_b32 s1, s1, 5
	s_lshl_b32 s0, s0, 7
	s_add_i32 s1, s1, s12
	s_add_i32 s8, s1, s0
	s_ashr_i32 s9, s8, 31
	s_lshl_b64 s[0:1], s[8:9], 2
	s_add_u32 s0, s15, s0
	s_addc_u32 s1, s16, s1
	s_mov_b32 s10, 0
	s_mov_b64 s[20:21], 0x10000
	s_mov_b64 s[22:23], 0x800000
.Lkn_j:
	v_mov_b64_e32 v[2:3], v[10:11]
	global_load_dwordx4 v[20:23], v[2:3], off
	v_lshl_add_u64 v[2:3], v[2:3], 0, s[20:21]
	global_load_dwordx4 v[24:27], v[2:3], off
	v_lshl_add_u64 v[2:3], v[2:3], 0, s[20:21]
	global_load_dwordx4 v[28:31], v[2:3], off
	v_lshl_add_u64 v[2:3], v[2:3], 0, s[20:21]
	global_load_dwordx4 v[32:35], v[2:3], off
	v_lshl_add_u64 v[2:3], v[2:3], 0, s[20:21]
	global_load_dwordx4 v[36:39], v[2:3], off
	v_lshl_add_u64 v[2:3], v[2:3], 0, s[20:21]
	global_load_dwordx4 v[40:43], v[2:3], off
	v_lshl_add_u64 v[2:3], v[2:3], 0, s[20:21]
	global_load_dwordx4 v[44:47], v[2:3], off
	v_lshl_add_u64 v[2:3], v[2:3], 0, s[20:21]
	global_load_dwordx4 v[48:51], v[2:3], off
	v_lshl_add_u64 v[2:3], v[2:3], 0, s[20:21]
	global_load_dwordx4 v[52:55], v[2:3], off
	v_lshl_add_u64 v[2:3], v[2:3], 0, s[20:21]
	global_load_dwordx4 v[56:59], v[2:3], off
	v_lshl_add_u64 v[2:3], v[2:3], 0, s[20:21]
	global_load_dwordx4 v[60:63], v[2:3], off
	v_lshl_add_u64 v[2:3], v[2:3], 0, s[20:21]
	global_load_dwordx4 v[64:67], v[2:3], off
	v_lshl_add_u64 v[2:3], v[2:3], 0, s[20:21]
	global_load_dwordx4 v[68:71], v[2:3], off
	v_lshl_add_u64 v[2:3], v[2:3], 0, s[20:21]
	global_load_dwordx4 v[72:75], v[2:3], off
	v_lshl_add_u64 v[2:3], v[2:3], 0, s[20:21]
	global_load_dwordx4 v[76:79], v[2:3], off
	v_lshl_add_u64 v[2:3], v[2:3], 0, s[20:21]
	global_load_dwordx4 v[80:83], v[2:3], off
	v_mov_b32_e32 v4, 0
	s_waitcnt vmcnt(15)
	v_lshlrev_b32_e32 v5, 16, v20
	v_and_b32_e32 v6, 0xffff0000, v20
	v_mul_f32_e32 v7, v5, v5
	v_fmac_f32_e32 v7, v6, v6
	v_lshlrev_b32_e32 v5, 16, v21
	v_and_b32_e32 v6, 0xffff0000, v21
	v_fmac_f32_e32 v7, v5, v5
	v_fmac_f32_e32 v7, v6, v6
	v_lshlrev_b32_e32 v5, 16, v22
	v_and_b32_e32 v6, 0xffff0000, v22
	v_fmac_f32_e32 v7, v5, v5
	v_fmac_f32_e32 v7, v6, v6
	v_lshlrev_b32_e32 v5, 16, v23
	v_and_b32_e32 v6, 0xffff0000, v23
	v_fmac_f32_e32 v7, v5, v5
	v_fmac_f32_e32 v7, v6, v6
	s_nop 1
	v_add_f32_dpp v5, v7, v7 quad_perm:[1,0,3,2] row_mask:0xf bank_mask:0xf
	s_nop 1
	v_add_f32_dpp v7, v5, v5 quad_perm:[2,3,0,1] row_mask:0xf bank_mask:0xf
	s_nop 1
	v_add_f32_dpp v5, v7, v7 row_half_mirror row_mask:0xf bank_mask:0xf
	s_nop 1
	v_add_f32_dpp v7, v5, v5 row_mirror row_mask:0xf bank_mask:0xf
	v_max_f32_e32 v4, v4, v7
	s_waitcnt vmcnt(14)
	v_lshlrev_b32_e32 v5, 16, v24
	v_and_b32_e32 v6, 0xffff0000, v24
	v_mul_f32_e32 v7, v5, v5
	v_fmac_f32_e32 v7, v6, v6
	v_lshlrev_b32_e32 v5, 16, v25
	v_and_b32_e32 v6, 0xffff0000, v25
	v_fmac_f32_e32 v7, v5, v5
	v_fmac_f32_e32 v7, v6, v6
	v_lshlrev_b32_e32 v5, 16, v26
	v_and_b32_e32 v6, 0xffff0000, v26
	v_fmac_f32_e32 v7, v5, v5
	v_fmac_f32_e32 v7, v6, v6
	v_lshlrev_b32_e32 v5, 16, v27
	v_and_b32_e32 v6, 0xffff0000, v27
	v_fmac_f32_e32 v7, v5, v5
	v_fmac_f32_e32 v7, v6, v6
	s_nop 1
	v_add_f32_dpp v5, v7, v7 quad_perm:[1,0,3,2] row_mask:0xf bank_mask:0xf
	s_nop 1
	v_add_f32_dpp v7, v5, v5 quad_perm:[2,3,0,1] row_mask:0xf bank_mask:0xf
	s_nop 1
	v_add_f32_dpp v5, v7, v7 row_half_mirror row_mask:0xf bank_mask:0xf
	s_nop 1
	v_add_f32_dpp v7, v5, v5 row_mirror row_mask:0xf bank_mask:0xf
	v_max_f32_e32 v4, v4, v7
	s_waitcnt vmcnt(13)
	v_lshlrev_b32_e32 v5, 16, v28
	v_and_b32_e32 v6, 0xffff0000, v28
	v_mul_f32_e32 v7, v5, v5
	v_fmac_f32_e32 v7, v6, v6
	v_lshlrev_b32_e32 v5, 16, v29
	v_and_b32_e32 v6, 0xffff0000, v29
	v_fmac_f32_e32 v7, v5, v5
	v_fmac_f32_e32 v7, v6, v6
	v_lshlrev_b32_e32 v5, 16, v30
	v_and_b32_e32 v6, 0xffff0000, v30
	v_fmac_f32_e32 v7, v5, v5
	v_fmac_f32_e32 v7, v6, v6
	v_lshlrev_b32_e32 v5, 16, v31
	v_and_b32_e32 v6, 0xffff0000, v31
	v_fmac_f32_e32 v7, v5, v5
	v_fmac_f32_e32 v7, v6, v6
	s_nop 1
	v_add_f32_dpp v5, v7, v7 quad_perm:[1,0,3,2] row_mask:0xf bank_mask:0xf
	s_nop 1
	v_add_f32_dpp v7, v5, v5 quad_perm:[2,3,0,1] row_mask:0xf bank_mask:0xf
	s_nop 1
	v_add_f32_dpp v5, v7, v7 row_half_mirror row_mask:0xf bank_mask:0xf
	s_nop 1
	v_add_f32_dpp v7, v5, v5 row_mirror row_mask:0xf bank_mask:0xf
	v_max_f32_e32 v4, v4, v7
	s_waitcnt vmcnt(12)
	v_lshlrev_b32_e32 v5, 16, v32
	v_and_b32_e32 v6, 0xffff0000, v32
	v_mul_f32_e32 v7, v5, v5
	v_fmac_f32_e32 v7, v6, v6
	v_lshlrev_b32_e32 v5, 16, v33
	v_and_b32_e32 v6, 0xffff0000, v33
	v_fmac_f32_e32 v7, v5, v5
	v_fmac_f32_e32 v7, v6, v6
	v_lshlrev_b32_e32 v5, 16, v34
	v_and_b32_e32 v6, 0xffff0000, v34
	v_fmac_f32_e32 v7, v5, v5
	v_fmac_f32_e32 v7, v6, v6
	v_lshlrev_b32_e32 v5, 16, v35
	v_and_b32_e32 v6, 0xffff0000, v35
	v_fmac_f32_e32 v7, v5, v5
	v_fmac_f32_e32 v7, v6, v6
	s_nop 1
	v_add_f32_dpp v5, v7, v7 quad_perm:[1,0,3,2] row_mask:0xf bank_mask:0xf
	s_nop 1
	v_add_f32_dpp v7, v5, v5 quad_perm:[2,3,0,1] row_mask:0xf bank_mask:0xf
	s_nop 1
	v_add_f32_dpp v5, v7, v7 row_half_mirror row_mask:0xf bank_mask:0xf
	s_nop 1
	v_add_f32_dpp v7, v5, v5 row_mirror row_mask:0xf bank_mask:0xf
	v_max_f32_e32 v4, v4, v7
	s_waitcnt vmcnt(11)
; __device__ __forceinline__ void phase_fox_cumsum(const Params& p, LAS unsigned char* lds) {
;     ...
;         for (int j = 0; j < 4; ++j) { const int key = quarter * 2048 + j * 512 + tid; const bf16_t* kr = Kp + ((size_t)b * SEQ + key) * 8192; float ss = 0.f;
; #pragma unroll
;             for (int c = 0; c < 16; ++c) { const u32x4 v = *(const u32x4*)(kr + c * 8);
;                 ss += bflo(v.x) * bflo(v.x) + bfhi(v.x) * bfhi(v.x) + bflo(v.y) * bflo(v.y) + bfhi(v.y) * bfhi(v.y) + bflo(v.z) * bflo(v.z) + bfhi(v.z) * bfhi(v.z) + bflo(v.w) * bflo(v.w) + bfhi(v.w) * bfhi(v.w); }
; #pragma unroll
;             for (int o = 1; o < 64; o <<= 1) ss = fmaxf(ss, __shfl_xor(ss, o));
;             if (lane == 0) KN[bh * 128 + quarter * 32 + j * 8 + wid] = ss; } }
	v_lshlrev_b32_e32 v5, 16, v36
	v_and_b32_e32 v6, 0xffff0000, v36
	v_mul_f32_e32 v7, v5, v5
	v_fmac_f32_e32 v7, v6, v6
	v_lshlrev_b32_e32 v5, 16, v37
	v_and_b32_e32 v6, 0xffff0000, v37
	v_fmac_f32_e32 v7, v5, v5
	v_fmac_f32_e32 v7, v6, v6
	v_lshlrev_b32_e32 v5, 16, v38
	v_and_b32_e32 v6, 0xffff0000, v38
	v_fmac_f32_e32 v7, v5, v5
	v_fmac_f32_e32 v7, v6, v6
	v_lshlrev_b32_e32 v5, 16, v39
	v_and_b32_e32 v6, 0xffff0000, v39
	v_fmac_f32_e32 v7, v5, v5
	v_fmac_f32_e32 v7, v6, v6
	s_nop 1
	v_add_f32_dpp v5, v7, v7 quad_perm:[1,0,3,2] row_mask:0xf bank_mask:0xf
	s_nop 1
	v_add_f32_dpp v7, v5, v5 quad_perm:[2,3,0,1] row_mask:0xf bank_mask:0xf
	s_nop 1
	v_add_f32_dpp v5, v7, v7 row_half_mirror row_mask:0xf bank_mask:0xf
	s_nop 1
	v_add_f32_dpp v7, v5, v5 row_mirror row_mask:0xf bank_mask:0xf
	v_max_f32_e32 v4, v4, v7
	s_waitcnt vmcnt(10)
	v_lshlrev_b32_e32 v5, 16, v40
	v_and_b32_e32 v6, 0xffff0000, v40
	v_mul_f32_e32 v7, v5, v5
	v_fmac_f32_e32 v7, v6, v6
	v_lshlrev_b32_e32 v5, 16, v41
	v_and_b32_e32 v6, 0xffff0000, v41
	v_fmac_f32_e32 v7, v5, v5
	v_fmac_f32_e32 v7, v6, v6
	v_lshlrev_b32_e32 v5, 16, v42
	v_and_b32_e32 v6, 0xffff0000, v42
	v_fmac_f32_e32 v7, v5, v5
	v_fmac_f32_e32 v7, v6, v6
	v_lshlrev_b32_e32 v5, 16, v43
	v_and_b32_e32 v6, 0xffff0000, v43
	v_fmac_f32_e32 v7, v5, v5
	v_fmac_f32_e32 v7, v6, v6
	s_nop 1
	v_add_f32_dpp v5, v7, v7 quad_perm:[1,0,3,2] row_mask:0xf bank_mask:0xf
	s_nop 1
	v_add_f32_dpp v7, v5, v5 quad_perm:[2,3,0,1] row_mask:0xf bank_mask:0xf
	s_nop 1
	v_add_f32_dpp v5, v7, v7 row_half_mirror row_mask:0xf bank_mask:0xf
	s_nop 1
	v_add_f32_dpp v7, v5, v5 row_mirror row_mask:0xf bank_mask:0xf
	v_max_f32_e32 v4, v4, v7
	s_waitcnt vmcnt(9)
	v_lshlrev_b32_e32 v5, 16, v44
	v_and_b32_e32 v6, 0xffff0000, v44
	v_mul_f32_e32 v7, v5, v5
	v_fmac_f32_e32 v7, v6, v6
	v_lshlrev_b32_e32 v5, 16, v45
	v_and_b32_e32 v6, 0xffff0000, v45
	v_fmac_f32_e32 v7, v5, v5
	v_fmac_f32_e32 v7, v6, v6
	v_lshlrev_b32_e32 v5, 16, v46
	v_and_b32_e32 v6, 0xffff0000, v46
	v_fmac_f32_e32 v7, v5, v5
	v_fmac_f32_e32 v7, v6, v6
	v_lshlrev_b32_e32 v5, 16, v47
	v_and_b32_e32 v6, 0xffff0000, v47
	v_fmac_f32_e32 v7, v5, v5
	v_fmac_f32_e32 v7, v6, v6
	s_nop 1
	v_add_f32_dpp v5, v7, v7 quad_perm:[1,0,3,2] row_mask:0xf bank_mask:0xf
	s_nop 1
	v_add_f32_dpp v7, v5, v5 quad_perm:[2,3,0,1] row_mask:0xf bank_mask:0xf
	s_nop 1
	v_add_f32_dpp v5, v7, v7 row_half_mirror row_mask:0xf bank_mask:0xf
	s_nop 1
	v_add_f32_dpp v7, v5, v5 row_mirror row_mask:0xf bank_mask:0xf
	v_max_f32_e32 v4, v4, v7
	s_waitcnt vmcnt(8)
	v_lshlrev_b32_e32 v5, 16, v48
	v_and_b32_e32 v6, 0xffff0000, v48
	v_mul_f32_e32 v7, v5, v5
	v_fmac_f32_e32 v7, v6, v6
	v_lshlrev_b32_e32 v5, 16, v49
	v_and_b32_e32 v6, 0xffff0000, v49
	v_fmac_f32_e32 v7, v5, v5
	v_fmac_f32_e32 v7, v6, v6
	v_lshlrev_b32_e32 v5, 16, v50
	v_and_b32_e32 v6, 0xffff0000, v50
	v_fmac_f32_e32 v7, v5, v5
	v_fmac_f32_e32 v7, v6, v6
	v_lshlrev_b32_e32 v5, 16, v51
	v_and_b32_e32 v6, 0xffff0000, v51
	v_fmac_f32_e32 v7, v5, v5
	v_fmac_f32_e32 v7, v6, v6
	s_nop 1
	v_add_f32_dpp v5, v7, v7 quad_perm:[1,0,3,2] row_mask:0xf bank_mask:0xf
	s_nop 1
	v_add_f32_dpp v7, v5, v5 quad_perm:[2,3,0,1] row_mask:0xf bank_mask:0xf
	s_nop 1
	v_add_f32_dpp v5, v7, v7 row_half_mirror row_mask:0xf bank_mask:0xf
	s_nop 1
	v_add_f32_dpp v7, v5, v5 row_mirror row_mask:0xf bank_mask:0xf
	v_max_f32_e32 v4, v4, v7
	s_waitcnt vmcnt(7)
	v_lshlrev_b32_e32 v5, 16, v52
	v_and_b32_e32 v6, 0xffff0000, v52
	v_mul_f32_e32 v7, v5, v5
	v_fmac_f32_e32 v7, v6, v6
	v_lshlrev_b32_e32 v5, 16, v53
	v_and_b32_e32 v6, 0xffff0000, v53
	v_fmac_f32_e32 v7, v5, v5
	v_fmac_f32_e32 v7, v6, v6
	v_lshlrev_b32_e32 v5, 16, v54
	v_and_b32_e32 v6, 0xffff0000, v54
	v_fmac_f32_e32 v7, v5, v5
	v_fmac_f32_e32 v7, v6, v6
	v_lshlrev_b32_e32 v5, 16, v55
	v_and_b32_e32 v6, 0xffff0000, v55
	v_fmac_f32_e32 v7, v5, v5
	v_fmac_f32_e32 v7, v6, v6
	s_nop 1
	v_add_f32_dpp v5, v7, v7 quad_perm:[1,0,3,2] row_mask:0xf bank_mask:0xf
	s_nop 1
	v_add_f32_dpp v7, v5, v5 quad_perm:[2,3,0,1] row_mask:0xf bank_mask:0xf
	s_nop 1
	v_add_f32_dpp v5, v7, v7 row_half_mirror row_mask:0xf bank_mask:0xf
	s_nop 1
	v_add_f32_dpp v7, v5, v5 row_mirror row_mask:0xf bank_mask:0xf
	v_max_f32_e32 v4, v4, v7
	s_waitcnt vmcnt(6)
	v_lshlrev_b32_e32 v5, 16, v56
	v_and_b32_e32 v6, 0xffff0000, v56
	v_mul_f32_e32 v7, v5, v5
	v_fmac_f32_e32 v7, v6, v6
	v_lshlrev_b32_e32 v5, 16, v57
	v_and_b32_e32 v6, 0xffff0000, v57
	v_fmac_f32_e32 v7, v5, v5
	v_fmac_f32_e32 v7, v6, v6
	v_lshlrev_b32_e32 v5, 16, v58
	v_and_b32_e32 v6, 0xffff0000, v58
	v_fmac_f32_e32 v7, v5, v5
	v_fmac_f32_e32 v7, v6, v6
	v_lshlrev_b32_e32 v5, 16, v59
	v_and_b32_e32 v6, 0xffff0000, v59
	v_fmac_f32_e32 v7, v5, v5
	v_fmac_f32_e32 v7, v6, v6
	s_nop 1
	v_add_f32_dpp v5, v7, v7 quad_perm:[1,0,3,2] row_mask:0xf bank_mask:0xf
	s_nop 1
	v_add_f32_dpp v7, v5, v5 quad_perm:[2,3,0,1] row_mask:0xf bank_mask:0xf
	s_nop 1
	v_add_f32_dpp v5, v7, v7 row_half_mirror row_mask:0xf bank_mask:0xf
	s_nop 1
	v_add_f32_dpp v7, v5, v5 row_mirror row_mask:0xf bank_mask:0xf
	v_max_f32_e32 v4, v4, v7
	s_waitcnt vmcnt(5)
; __device__ __forceinline__ void phase_fox_cumsum(const Params& p, LAS unsigned char* lds) {
;     ...
;         for (int j = 0; j < 4; ++j) { const int key = quarter * 2048 + j * 512 + tid; const bf16_t* kr = Kp + ((size_t)b * SEQ + key) * 8192; float ss = 0.f;
; #pragma unroll
;             for (int c = 0; c < 16; ++c) { const u32x4 v = *(const u32x4*)(kr + c * 8);
;                 ss += bflo(v.x) * bflo(v.x) + bfhi(v.x) * bfhi(v.x) + bflo(v.y) * bflo(v.y) + bfhi(v.y) * bfhi(v.y) + bflo(v.z) * bflo(v.z) + bfhi(v.z) * bfhi(v.z) + bflo(v.w) * bflo(v.w) + bfhi(v.w) * bfhi(v.w); }
; #pragma unroll
;             for (int o = 1; o < 64; o <<= 1) ss = fmaxf(ss, __shfl_xor(ss, o));
;             if (lane == 0) KN[bh * 128 + quarter * 32 + j * 8 + wid] = ss; } }
	v_lshlrev_b32_e32 v5, 16, v60
	v_and_b32_e32 v6, 0xffff0000, v60
	v_mul_f32_e32 v7, v5, v5
	v_fmac_f32_e32 v7, v6, v6
	v_lshlrev_b32_e32 v5, 16, v61
	v_and_b32_e32 v6, 0xffff0000, v61
	v_fmac_f32_e32 v7, v5, v5
	v_fmac_f32_e32 v7, v6, v6
	v_lshlrev_b32_e32 v5, 16, v62
	v_and_b32_e32 v6, 0xffff0000, v62
	v_fmac_f32_e32 v7, v5, v5
	v_fmac_f32_e32 v7, v6, v6
	v_lshlrev_b32_e32 v5, 16, v63
	v_and_b32_e32 v6, 0xffff0000, v63
	v_fmac_f32_e32 v7, v5, v5
	v_fmac_f32_e32 v7, v6, v6
	s_nop 1
	v_add_f32_dpp v5, v7, v7 quad_perm:[1,0,3,2] row_mask:0xf bank_mask:0xf
	s_nop 1
	v_add_f32_dpp v7, v5, v5 quad_perm:[2,3,0,1] row_mask:0xf bank_mask:0xf
	s_nop 1
	v_add_f32_dpp v5, v7, v7 row_half_mirror row_mask:0xf bank_mask:0xf
	s_nop 1
	v_add_f32_dpp v7, v5, v5 row_mirror row_mask:0xf bank_mask:0xf
	v_max_f32_e32 v4, v4, v7
	s_waitcnt vmcnt(4)
	v_lshlrev_b32_e32 v5, 16, v64
	v_and_b32_e32 v6, 0xffff0000, v64
	v_mul_f32_e32 v7, v5, v5
	v_fmac_f32_e32 v7, v6, v6
	v_lshlrev_b32_e32 v5, 16, v65
	v_and_b32_e32 v6, 0xffff0000, v65
	v_fmac_f32_e32 v7, v5, v5
	v_fmac_f32_e32 v7, v6, v6
	v_lshlrev_b32_e32 v5, 16, v66
	v_and_b32_e32 v6, 0xffff0000, v66
	v_fmac_f32_e32 v7, v5, v5
	v_fmac_f32_e32 v7, v6, v6
	v_lshlrev_b32_e32 v5, 16, v67
	v_and_b32_e32 v6, 0xffff0000, v67
	v_fmac_f32_e32 v7, v5, v5
	v_fmac_f32_e32 v7, v6, v6
	s_nop 1
	v_add_f32_dpp v5, v7, v7 quad_perm:[1,0,3,2] row_mask:0xf bank_mask:0xf
	s_nop 1
	v_add_f32_dpp v7, v5, v5 quad_perm:[2,3,0,1] row_mask:0xf bank_mask:0xf
	s_nop 1
	v_add_f32_dpp v5, v7, v7 row_half_mirror row_mask:0xf bank_mask:0xf
	s_nop 1
	v_add_f32_dpp v7, v5, v5 row_mirror row_mask:0xf bank_mask:0xf
	v_max_f32_e32 v4, v4, v7
	s_waitcnt vmcnt(3)
	v_lshlrev_b32_e32 v5, 16, v68
	v_and_b32_e32 v6, 0xffff0000, v68
	v_mul_f32_e32 v7, v5, v5
	v_fmac_f32_e32 v7, v6, v6
	v_lshlrev_b32_e32 v5, 16, v69
	v_and_b32_e32 v6, 0xffff0000, v69
	v_fmac_f32_e32 v7, v5, v5
	v_fmac_f32_e32 v7, v6, v6
	v_lshlrev_b32_e32 v5, 16, v70
	v_and_b32_e32 v6, 0xffff0000, v70
	v_fmac_f32_e32 v7, v5, v5
	v_fmac_f32_e32 v7, v6, v6
	v_lshlrev_b32_e32 v5, 16, v71
	v_and_b32_e32 v6, 0xffff0000, v71
	v_fmac_f32_e32 v7, v5, v5
	v_fmac_f32_e32 v7, v6, v6
	s_nop 1
	v_add_f32_dpp v5, v7, v7 quad_perm:[1,0,3,2] row_mask:0xf bank_mask:0xf
	s_nop 1
	v_add_f32_dpp v7, v5, v5 quad_perm:[2,3,0,1] row_mask:0xf bank_mask:0xf
	s_nop 1
	v_add_f32_dpp v5, v7, v7 row_half_mirror row_mask:0xf bank_mask:0xf
	s_nop 1
	v_add_f32_dpp v7, v5, v5 row_mirror row_mask:0xf bank_mask:0xf
	v_max_f32_e32 v4, v4, v7
	s_waitcnt vmcnt(2)
	v_lshlrev_b32_e32 v5, 16, v72
	v_and_b32_e32 v6, 0xffff0000, v72
	v_mul_f32_e32 v7, v5, v5
	v_fmac_f32_e32 v7, v6, v6
	v_lshlrev_b32_e32 v5, 16, v73
	v_and_b32_e32 v6, 0xffff0000, v73
	v_fmac_f32_e32 v7, v5, v5
	v_fmac_f32_e32 v7, v6, v6
	v_lshlrev_b32_e32 v5, 16, v74
	v_and_b32_e32 v6, 0xffff0000, v74
	v_fmac_f32_e32 v7, v5, v5
	v_fmac_f32_e32 v7, v6, v6
	v_lshlrev_b32_e32 v5, 16, v75
	v_and_b32_e32 v6, 0xffff0000, v75
	v_fmac_f32_e32 v7, v5, v5
	v_fmac_f32_e32 v7, v6, v6
	s_nop 1
	v_add_f32_dpp v5, v7, v7 quad_perm:[1,0,3,2] row_mask:0xf bank_mask:0xf
	s_nop 1
	v_add_f32_dpp v7, v5, v5 quad_perm:[2,3,0,1] row_mask:0xf bank_mask:0xf
	s_nop 1
	v_add_f32_dpp v5, v7, v7 row_half_mirror row_mask:0xf bank_mask:0xf
	s_nop 1
	v_add_f32_dpp v7, v5, v5 row_mirror row_mask:0xf bank_mask:0xf
	v_max_f32_e32 v4, v4, v7
	s_waitcnt vmcnt(1)
	v_lshlrev_b32_e32 v5, 16, v76
	v_and_b32_e32 v6, 0xffff0000, v76
	v_mul_f32_e32 v7, v5, v5
	v_fmac_f32_e32 v7, v6, v6
	v_lshlrev_b32_e32 v5, 16, v77
	v_and_b32_e32 v6, 0xffff0000, v77
	v_fmac_f32_e32 v7, v5, v5
	v_fmac_f32_e32 v7, v6, v6
	v_lshlrev_b32_e32 v5, 16, v78
	v_and_b32_e32 v6, 0xffff0000, v78
	v_fmac_f32_e32 v7, v5, v5
	v_fmac_f32_e32 v7, v6, v6
	v_lshlrev_b32_e32 v5, 16, v79
	v_and_b32_e32 v6, 0xffff0000, v79
	v_fmac_f32_e32 v7, v5, v5
	v_fmac_f32_e32 v7, v6, v6
	s_nop 1
	v_add_f32_dpp v5, v7, v7 quad_perm:[1,0,3,2] row_mask:0xf bank_mask:0xf
	s_nop 1
	v_add_f32_dpp v7, v5, v5 quad_perm:[2,3,0,1] row_mask:0xf bank_mask:0xf
	s_nop 1
	v_add_f32_dpp v5, v7, v7 row_half_mirror row_mask:0xf bank_mask:0xf
	s_nop 1
	v_add_f32_dpp v7, v5, v5 row_mirror row_mask:0xf bank_mask:0xf
	v_max_f32_e32 v4, v4, v7
	s_waitcnt vmcnt(0)
	v_lshlrev_b32_e32 v5, 16, v80
	v_and_b32_e32 v6, 0xffff0000, v80
	v_mul_f32_e32 v7, v5, v5
	v_fmac_f32_e32 v7, v6, v6
	v_lshlrev_b32_e32 v5, 16, v81
	v_and_b32_e32 v6, 0xffff0000, v81
	v_fmac_f32_e32 v7, v5, v5
	v_fmac_f32_e32 v7, v6, v6
	v_lshlrev_b32_e32 v5, 16, v82
	v_and_b32_e32 v6, 0xffff0000, v82
	v_fmac_f32_e32 v7, v5, v5
	v_fmac_f32_e32 v7, v6, v6
	v_lshlrev_b32_e32 v5, 16, v83
	v_and_b32_e32 v6, 0xffff0000, v83
	v_fmac_f32_e32 v7, v5, v5
	v_fmac_f32_e32 v7, v6, v6
	s_nop 1
	v_add_f32_dpp v5, v7, v7 quad_perm:[1,0,3,2] row_mask:0xf bank_mask:0xf
	s_nop 1
	v_add_f32_dpp v7, v5, v5 quad_perm:[2,3,0,1] row_mask:0xf bank_mask:0xf
	s_nop 1
	v_add_f32_dpp v5, v7, v7 row_half_mirror row_mask:0xf bank_mask:0xf
	s_nop 1
	v_add_f32_dpp v7, v5, v5 row_mirror row_mask:0xf bank_mask:0xf
	v_max_f32_e32 v4, v4, v7
	v_mov_b32_e32 v5, v4
	s_nop 1
	v_permlane16_swap_b32_e32 v4, v5
	s_nop 1
	v_max_f32_e32 v4, v4, v5
	v_mov_b32_e32 v5, v4
	s_nop 1
	v_permlane32_swap_b32_e32 v4, v5
	s_nop 1
	v_max_f32_e32 v4, v4, v5
	s_and_saveexec_b64 s[24:25], vcc
	global_store_dword v12, v4, s[0:1]
	s_or_b64 exec, exec, s[24:25]
	s_add_u32 s0, s0, 32
	s_addc_u32 s1, s1, 0
	v_lshl_add_u64 v[10:11], v[10:11], 0, s[22:23]
	s_add_i32 s10, s10, 1
	s_cmp_lt_u32 s10, 4
	s_cbranch_scc1 .Lkn_j
	s_branch .LBB0_920

; __device__ __forceinline__ unsigned pk2(float lo, float hi) { f32x2 v = {lo, hi}; bf16x2_t b = __builtin_convertvector(v, bf16x2_t); return __builtin_bit_cast(unsigned, b); }
; __device__ __forceinline__ float silu_f(float z) { return z * __builtin_amdgcn_rcpf(1.0f + __expf(-z)); }
; __device__ __forceinline__ int launder_v(int x) { asm volatile("" : "+v"(x)); return x; }
; __device__ __forceinline__ int launder_s(int x) { asm volatile("" : "+s"(x)); return x; }
; __device__ __forceinline__ float swap_add(float v) { unsigned a = __builtin_bit_cast(unsigned, v), b = a; asm volatile("s_nop 1\n\tv_permlane32_swap_b32 %0, %1\n\ts_nop 1" : "+v"(a), "+v"(b)); return __builtin_bit_cast(float, a) + __builtin_bit_cast(float, b); }
; template <int MODE>
; __device__ __forceinline__ void attn_unit(LAS unsigned char* lds, const bf16_t* __restrict__ qkvz, bf16_t* __restrict__ A2, const int b, const int hd, const int qb, const AttnX& X, const int tid) {
;     ...
;     const float l_tot = swap_add(l_run);
;     const float inv = 1.0f / l_tot;
;     const int lane_e = launder_v(lane);
;     const size_t trow = (size_t)launder_s(b) * SEQ + launder_s(q0w) + (lane_e & 31);
;     if (MODE != 0) {
;         const int hh_e = lane_e >> 5;
;         u32x2 zz[NDT * 4];
; #pragma unroll
;         for (int d = 0; d < NDT; ++d)
; #pragma unroll
;             for (int i4 = 0; i4 < 4; ++i4) zz[d * 4 + i4] = *(const u32x2*)(qkvz + trow * LD + zcol + 32 * d + 8 * i4 + 4 * hh_e);
; #pragma unroll
;         for (int d = 0; d < NDT; ++d)
; #pragma unroll
;             for (int i4 = 0; i4 < 4; ++i4) { const int dd = 32 * d + 8 * i4 + 4 * hh_e; const u32x2 z2 = zz[d * 4 + i4];
;                 u32x2 w;
;                 w.x = pk2(O[d][4 * i4 + 0] * inv * silu_f(bflo(z2.x)), O[d][4 * i4 + 1] * inv * silu_f(bfhi(z2.x)));
;                 w.y = pk2(O[d][4 * i4 + 2] * inv * silu_f(bflo(z2.y)), O[d][4 * i4 + 3] * inv * silu_f(bfhi(z2.y)));
;                 *(u32x2*)(A2 + trow * DM + hd * C::DV + dd) = w; }
.LBB0_1003:
	s_or_b64 exec, exec, s[92:93]
	v_readlane_b32 s0, v254, 51
	v_readlane_b32 s1, v254, 52
	v_cmp_eq_u32_e32 vcc, 0, v212
	s_and_saveexec_b64 s[2:3], vcc
	s_cbranch_execz .Lfox_pf_skip
	v_mov_b32_e32 v250, 0x93a0080
	v_mov_b32_e32 v251, 1
	s_nop 1
	global_atomic_add v250, v250, v251, s[0:1] sc0
.Lfox_pf_skip:
	s_or_b64 exec, exec, s[2:3]
	v_mov_b32_e32 v74, v190
	v_mov_b32_e32 v70, v161
	s_nop 1
	v_permlane32_swap_b32 v190, v74
	s_nop 1
	s_ashr_i32 s15, s14, 31
	s_lshl_b64 s[0:1], s[14:15], 13
	s_ashr_i32 s2, s13, 31
	s_add_u32 s0, s0, s13
	v_and_b32_e32 v0, 31, v70
	s_addc_u32 s1, s1, s2
	v_lshl_add_u64 v[66:67], s[0:1], 0, v[0:1]
	v_readlane_b32 s84, v255, 7
	v_ashrrev_i32_e32 v0, 3, v70
	v_lshlrev_b64 v[68:69], 14, v[66:67]
	v_readlane_b32 s85, v255, 8
	v_and_b32_e32 v70, -4, v0
	s_mov_b32 s13, s89
	v_lshl_add_u64 v[68:69], s[84:85], 0, v[68:69]
	v_ashrrev_i32_e32 v71, 31, v70
	v_lshl_add_u64 v[68:69], v[68:69], 0, s[12:13]
	v_lshlrev_b64 v[70:71], 1, v[70:71]
	v_lshl_add_u64 v[68:69], v[68:69], 0, v[70:71]
	s_movk_i32 s0, 0x3000
	v_add_co_u32_e32 v72, vcc, s0, v68
	s_mov_b64 s[0:1], 0x3000
	s_nop 0
	v_addc_co_u32_e32 v73, vcc, 0, v69, vcc
	global_load_dwordx2 v[90:91], v[72:73], off
	v_lshl_add_u64 v[68:69], v[68:69], 0, s[0:1]
	global_load_dwordx2 v[92:93], v[68:69], off offset:16
	global_load_dwordx2 v[94:95], v[68:69], off offset:32
	v_add_f32_e32 v0, v190, v74
	v_div_scale_f32 v100, s[0:1], v0, v0, 1.0
	v_rcp_f32_e32 v101, v100
	v_readlane_b32 s94, v255, 5
	v_lshlrev_b64 v[66:67], 12, v[66:67]
	v_readlane_b32 s95, v255, 6
	v_fma_f32 v72, -v100, v101, 1.0
	v_fmac_f32_e32 v101, v72, v101
	v_lshl_add_u64 v[66:67], s[94:95], 0, v[66:67]
	v_lshl_add_u64 v[66:67], v[66:67], 0, s[12:13]
	v_lshl_add_u64 v[66:67], v[66:67], 0, v[70:71]
	global_load_dwordx2 v[96:97], v[68:69], off offset:48
	global_load_dwordx2 v[98:99], v[68:69], off offset:64
	global_load_dwordx2 v[88:89], v[68:69], off offset:80
	global_load_dwordx2 v[86:87], v[68:69], off offset:96
	global_load_dwordx2 v[84:85], v[68:69], off offset:112
	global_load_dwordx2 v[82:83], v[68:69], off offset:128
	global_load_dwordx2 v[80:81], v[68:69], off offset:144
	global_load_dwordx2 v[78:79], v[68:69], off offset:160
	global_load_dwordx2 v[76:77], v[68:69], off offset:176
	global_load_dwordx2 v[74:75], v[68:69], off offset:192
	global_load_dwordx2 v[72:73], v[68:69], off offset:208
	global_load_dwordx2 v[70:71], v[68:69], off offset:224
	s_nop 0
	global_load_dwordx2 v[68:69], v[68:69], off offset:240
	v_div_scale_f32 v102, vcc, 1.0, v0, 1.0
	v_mul_f32_e32 v103, v102, v101
	v_fma_f32 v104, -v100, v103, v102
	v_fmac_f32_e32 v103, v104, v101
	v_fma_f32 v100, -v100, v103, v102
	v_div_fmas_f32 v100, v100, v101, v103
	v_div_fixup_f32 v0, v100, v0, 1.0
	v_pk_mul_f32 v[50:51], v[50:51], v[0:1] op_sel_hi:[1,0]
	v_pk_mul_f32 v[52:53], v[52:53], v[0:1] op_sel_hi:[1,0]
	v_pk_mul_f32 v[54:55], v[54:55], v[0:1] op_sel_hi:[1,0]
	v_pk_mul_f32 v[34:35], v[34:35], v[0:1] op_sel_hi:[1,0]
	v_pk_mul_f32 v[36:37], v[36:37], v[0:1] op_sel_hi:[1,0]
	v_pk_mul_f32 v[38:39], v[38:39], v[0:1] op_sel_hi:[1,0]
	v_pk_mul_f32 v[18:19], v[18:19], v[0:1] op_sel_hi:[1,0]
	v_pk_mul_f32 v[20:21], v[20:21], v[0:1] op_sel_hi:[1,0]
	v_pk_mul_f32 v[22:23], v[22:23], v[0:1] op_sel_hi:[1,0]
	v_pk_mul_f32 v[2:3], v[2:3], v[0:1] op_sel_hi:[1,0]
	v_pk_mul_f32 v[4:5], v[4:5], v[0:1] op_sel_hi:[1,0]
	v_pk_mul_f32 v[6:7], v[6:7], v[0:1] op_sel_hi:[1,0]
	v_readlane_b32 s0, v254, 47
	v_readlane_b32 s28, v255, 9
	v_readlane_b32 s92, v255, 4
	v_readlane_b32 s29, v255, 10
	s_waitcnt vmcnt(15)
	v_lshlrev_b32_e32 v100, 16, v90
	v_and_b32_e32 v101, 0xffff0000, v90
	v_lshlrev_b32_e32 v90, 16, v91
	v_and_b32_e32 v91, 0xffff0000, v91
	v_mul_f32_e32 v104, 0xbfb8aa3b, v100
	v_mul_f32_e32 v105, 0xbfb8aa3b, v101
	v_mul_f32_e32 v106, 0xbfb8aa3b, v90
	v_mul_f32_e32 v107, 0xbfb8aa3b, v91
	v_exp_f32_e32 v104, v104
	v_exp_f32_e32 v105, v105
	v_exp_f32_e32 v106, v106
	v_exp_f32_e32 v107, v107
	v_add_f32_e32 v104, 1.0, v104
	v_add_f32_e32 v105, 1.0, v105
	v_add_f32_e32 v106, 1.0, v106
	v_add_f32_e32 v107, 1.0, v107
	v_rcp_f32_e32 v104, v104
	v_rcp_f32_e32 v105, v105
	v_rcp_f32_e32 v106, v106
	v_rcp_f32_e32 v107, v107
	s_waitcnt vmcnt(14)
	v_lshlrev_b32_e32 v102, 16, v92
	v_and_b32_e32 v103, 0xffff0000, v92
	v_lshlrev_b32_e32 v92, 16, v93
	v_and_b32_e32 v93, 0xffff0000, v93
	v_mul_f32_e32 v108, 0xbfb8aa3b, v102
	v_mul_f32_e32 v109, 0xbfb8aa3b, v103
	v_pk_mul_f32 v[100:101], v[104:105], v[100:101]
	v_pk_mul_f32 v[90:91], v[106:107], v[90:91]
	v_mul_f32_e32 v110, 0xbfb8aa3b, v92
	v_mul_f32_e32 v111, 0xbfb8aa3b, v93
	v_exp_f32_e32 v108, v108
	v_exp_f32_e32 v109, v109
	v_pk_mul_f32 v[50:51], v[50:51], v[100:101]
	v_pk_mul_f32 v[52:53], v[52:53], v[90:91]
	v_exp_f32_e32 v110, v110
	v_cvt_pk_bf16_f32 v50, v50, v51
	v_cvt_pk_bf16_f32 v51, v52, v53
	v_exp_f32_e32 v53, v111
	v_add_f32_e32 v108, 1.0, v108
	v_add_f32_e32 v109, 1.0, v109
	v_rcp_f32_e32 v108, v108
	v_rcp_f32_e32 v109, v109
	v_add_f32_e32 v52, 1.0, v110
	v_add_f32_e32 v53, 1.0, v53
	v_rcp_f32_e32 v52, v52
	v_rcp_f32_e32 v53, v53
	global_store_dwordx2 v[66:67], v[50:51], off
	v_pk_mul_f32 v[50:51], v[108:109], v[102:103]
	v_pk_mul_f32 v[52:53], v[52:53], v[92:93]
	v_pk_mul_f32 v[50:51], v[54:55], v[50:51]
	v_pk_mul_f32 v[54:55], v[56:57], v[0:1] op_sel_hi:[1,0]
	v_cvt_pk_bf16_f32 v50, v50, v51
	v_pk_mul_f32 v[52:53], v[54:55], v[52:53]
	s_waitcnt vmcnt(14)
; __device__ __forceinline__ unsigned pk2(float lo, float hi) { f32x2 v = {lo, hi}; bf16x2_t b = __builtin_convertvector(v, bf16x2_t); return __builtin_bit_cast(unsigned, b); }
; __device__ __forceinline__ float silu_f(float z) { return z * __builtin_amdgcn_rcpf(1.0f + __expf(-z)); }
; template <int MODE>
; __device__ __forceinline__ void attn_unit(LAS unsigned char* lds, const bf16_t* __restrict__ qkvz, bf16_t* __restrict__ A2, const int b, const int hd, const int qb, const AttnX& X, const int tid) {
;     ...
;         for (int d = 0; d < NDT; ++d)
; #pragma unroll
;             for (int i4 = 0; i4 < 4; ++i4) { const int dd = 32 * d + 8 * i4 + 4 * hh_e; const u32x2 z2 = zz[d * 4 + i4];
;                 u32x2 w;
;                 w.x = pk2(O[d][4 * i4 + 0] * inv * silu_f(bflo(z2.x)), O[d][4 * i4 + 1] * inv * silu_f(bfhi(z2.x)));
;                 w.y = pk2(O[d][4 * i4 + 2] * inv * silu_f(bflo(z2.y)), O[d][4 * i4 + 3] * inv * silu_f(bfhi(z2.y)));
;                 *(u32x2*)(A2 + trow * DM + hd * C::DV + dd) = w; }
	v_lshlrev_b32_e32 v56, 16, v95
	v_cvt_pk_bf16_f32 v51, v52, v53
	global_store_dwordx2 v[66:67], v[50:51], off offset:16
	v_lshlrev_b32_e32 v50, 16, v94
	v_mul_f32_e32 v51, 0xbfb8aa3b, v50
	v_exp_f32_e32 v52, v51
	v_and_b32_e32 v51, 0xffff0000, v94
	v_mul_f32_e32 v53, 0xbfb8aa3b, v51
	v_exp_f32_e32 v53, v53
	v_and_b32_e32 v57, 0xffff0000, v95
	v_add_f32_e32 v52, 1.0, v52
	v_pk_mul_f32 v[54:55], v[58:59], v[0:1] op_sel_hi:[1,0]
	v_add_f32_e32 v53, 1.0, v53
	v_mul_f32_e32 v58, 0xbfb8aa3b, v56
	v_mul_f32_e32 v59, 0xbfb8aa3b, v57
	v_rcp_f32_e32 v52, v52
	v_rcp_f32_e32 v53, v53
	v_exp_f32_e32 v58, v58
	v_exp_f32_e32 v59, v59
	v_pk_mul_f32 v[50:51], v[52:53], v[50:51]
	v_add_f32_e32 v52, 1.0, v58
	v_add_f32_e32 v53, 1.0, v59
	v_rcp_f32_e32 v52, v52
	v_rcp_f32_e32 v53, v53
	v_pk_mul_f32 v[50:51], v[54:55], v[50:51]
	v_pk_mul_f32 v[54:55], v[60:61], v[0:1] op_sel_hi:[1,0]
	v_cvt_pk_bf16_f32 v50, v50, v51
	v_pk_mul_f32 v[52:53], v[52:53], v[56:57]
	s_waitcnt vmcnt(14)
	v_lshlrev_b32_e32 v56, 16, v97
	v_pk_mul_f32 v[52:53], v[54:55], v[52:53]
	v_and_b32_e32 v57, 0xffff0000, v97
	v_cvt_pk_bf16_f32 v51, v52, v53
	global_store_dwordx2 v[66:67], v[50:51], off offset:32
	v_lshlrev_b32_e32 v50, 16, v96
	v_mul_f32_e32 v51, 0xbfb8aa3b, v50
	v_exp_f32_e32 v52, v51
	v_and_b32_e32 v51, 0xffff0000, v96
	v_mul_f32_e32 v53, 0xbfb8aa3b, v51
	v_exp_f32_e32 v53, v53
	v_add_f32_e32 v52, 1.0, v52
	v_mul_f32_e32 v58, 0xbfb8aa3b, v56
	v_mul_f32_e32 v59, 0xbfb8aa3b, v57
	v_add_f32_e32 v53, 1.0, v53
	v_rcp_f32_e32 v52, v52
	v_rcp_f32_e32 v53, v53
	v_exp_f32_e32 v58, v58
	v_exp_f32_e32 v59, v59
	v_pk_mul_f32 v[54:55], v[62:63], v[0:1] op_sel_hi:[1,0]
	v_pk_mul_f32 v[50:51], v[52:53], v[50:51]
	v_add_f32_e32 v52, 1.0, v58
	v_add_f32_e32 v53, 1.0, v59
	v_rcp_f32_e32 v52, v52
	v_rcp_f32_e32 v53, v53
	v_pk_mul_f32 v[50:51], v[54:55], v[50:51]
	v_pk_mul_f32 v[54:55], v[64:65], v[0:1] op_sel_hi:[1,0]
	v_cvt_pk_bf16_f32 v50, v50, v51
	v_pk_mul_f32 v[52:53], v[52:53], v[56:57]
	s_nop 0
	v_pk_mul_f32 v[52:53], v[54:55], v[52:53]
	s_waitcnt vmcnt(14)
	v_lshlrev_b32_e32 v54, 16, v99
	v_cvt_pk_bf16_f32 v51, v52, v53
	global_store_dwordx2 v[66:67], v[50:51], off offset:48
	v_lshlrev_b32_e32 v50, 16, v98
	v_mul_f32_e32 v51, 0xbfb8aa3b, v50
	v_exp_f32_e32 v52, v51
	v_and_b32_e32 v51, 0xffff0000, v98
	v_mul_f32_e32 v53, 0xbfb8aa3b, v51
	v_exp_f32_e32 v53, v53
	v_and_b32_e32 v55, 0xffff0000, v99
	v_add_f32_e32 v52, 1.0, v52
	v_mul_f32_e32 v56, 0xbfb8aa3b, v54
	v_add_f32_e32 v53, 1.0, v53
	v_mul_f32_e32 v57, 0xbfb8aa3b, v55
	v_rcp_f32_e32 v52, v52
	v_rcp_f32_e32 v53, v53
	v_exp_f32_e32 v56, v56
	v_exp_f32_e32 v57, v57
	v_pk_mul_f32 v[50:51], v[52:53], v[50:51]
	v_add_f32_e32 v52, 1.0, v56
	v_add_f32_e32 v53, 1.0, v57
	v_rcp_f32_e32 v52, v52
	v_rcp_f32_e32 v53, v53
	v_pk_mul_f32 v[34:35], v[34:35], v[50:51]
	v_pk_mul_f32 v[50:51], v[52:53], v[54:55]
	s_nop 0
	v_pk_mul_f32 v[36:37], v[36:37], v[50:51]
	v_cvt_pk_bf16_f32 v34, v34, v35
	v_cvt_pk_bf16_f32 v35, v36, v37
	global_store_dwordx2 v[66:67], v[34:35], off offset:64
	s_waitcnt vmcnt(15)
	v_lshlrev_b32_e32 v34, 16, v88
	v_mul_f32_e32 v35, 0xbfb8aa3b, v34
	v_exp_f32_e32 v36, v35
	v_and_b32_e32 v35, 0xffff0000, v88
	v_mul_f32_e32 v37, 0xbfb8aa3b, v35
	v_exp_f32_e32 v37, v37
	v_lshlrev_b32_e32 v50, 16, v89
	v_and_b32_e32 v51, 0xffff0000, v89
	v_add_f32_e32 v36, 1.0, v36
	v_add_f32_e32 v37, 1.0, v37
	v_mul_f32_e32 v52, 0xbfb8aa3b, v50
	v_mul_f32_e32 v53, 0xbfb8aa3b, v51
	v_rcp_f32_e32 v36, v36
	v_rcp_f32_e32 v37, v37
	v_exp_f32_e32 v52, v52
	v_exp_f32_e32 v53, v53
	v_pk_mul_f32 v[34:35], v[36:37], v[34:35]
	v_add_f32_e32 v36, 1.0, v52
	v_add_f32_e32 v37, 1.0, v53
	v_rcp_f32_e32 v36, v36
	v_rcp_f32_e32 v37, v37
	v_pk_mul_f32 v[34:35], v[38:39], v[34:35]
	v_pk_mul_f32 v[38:39], v[40:41], v[0:1] op_sel_hi:[1,0]
	v_cvt_pk_bf16_f32 v34, v34, v35
	v_pk_mul_f32 v[36:37], v[36:37], v[50:51]
	s_waitcnt vmcnt(14)
	v_lshlrev_b32_e32 v40, 16, v87
	v_pk_mul_f32 v[36:37], v[38:39], v[36:37]
	v_and_b32_e32 v41, 0xffff0000, v87
	v_cvt_pk_bf16_f32 v35, v36, v37
	global_store_dwordx2 v[66:67], v[34:35], off offset:80
	v_lshlrev_b32_e32 v34, 16, v86
	v_mul_f32_e32 v35, 0xbfb8aa3b, v34
	v_exp_f32_e32 v36, v35
	v_and_b32_e32 v35, 0xffff0000, v86
	v_mul_f32_e32 v37, 0xbfb8aa3b, v35
	v_exp_f32_e32 v37, v37
	v_add_f32_e32 v36, 1.0, v36
	v_pk_mul_f32 v[38:39], v[42:43], v[0:1] op_sel_hi:[1,0]
	v_mul_f32_e32 v42, 0xbfb8aa3b, v40
	v_add_f32_e32 v37, 1.0, v37
	v_mul_f32_e32 v43, 0xbfb8aa3b, v41
	v_rcp_f32_e32 v36, v36
	v_rcp_f32_e32 v37, v37
	v_exp_f32_e32 v42, v42
	v_exp_f32_e32 v43, v43
	v_pk_mul_f32 v[34:35], v[36:37], v[34:35]
	v_add_f32_e32 v36, 1.0, v42
	v_add_f32_e32 v37, 1.0, v43
	v_rcp_f32_e32 v36, v36
	v_rcp_f32_e32 v37, v37
	v_pk_mul_f32 v[34:35], v[38:39], v[34:35]
	v_pk_mul_f32 v[38:39], v[44:45], v[0:1] op_sel_hi:[1,0]
	v_cvt_pk_bf16_f32 v34, v34, v35
	v_pk_mul_f32 v[36:37], v[36:37], v[40:41]
	s_waitcnt vmcnt(14)
	v_lshlrev_b32_e32 v40, 16, v85
	v_pk_mul_f32 v[36:37], v[38:39], v[36:37]
	v_and_b32_e32 v41, 0xffff0000, v85
	v_cvt_pk_bf16_f32 v35, v36, v37
	global_store_dwordx2 v[66:67], v[34:35], off offset:96
	v_lshlrev_b32_e32 v34, 16, v84
	v_mul_f32_e32 v35, 0xbfb8aa3b, v34
	v_exp_f32_e32 v36, v35
	v_and_b32_e32 v35, 0xffff0000, v84
	v_mul_f32_e32 v37, 0xbfb8aa3b, v35
	v_exp_f32_e32 v37, v37
	v_add_f32_e32 v36, 1.0, v36
	v_mul_f32_e32 v42, 0xbfb8aa3b, v40
	v_mul_f32_e32 v43, 0xbfb8aa3b, v41
	v_add_f32_e32 v37, 1.0, v37
	v_rcp_f32_e32 v36, v36
	v_rcp_f32_e32 v37, v37
	v_exp_f32_e32 v42, v42
	v_exp_f32_e32 v43, v43
	v_pk_mul_f32 v[38:39], v[46:47], v[0:1] op_sel_hi:[1,0]
	v_pk_mul_f32 v[34:35], v[36:37], v[34:35]
	v_add_f32_e32 v36, 1.0, v42
	v_add_f32_e32 v37, 1.0, v43
	v_rcp_f32_e32 v36, v36
	v_rcp_f32_e32 v37, v37
	v_pk_mul_f32 v[34:35], v[38:39], v[34:35]
	v_pk_mul_f32 v[38:39], v[48:49], v[0:1] op_sel_hi:[1,0]
	v_cvt_pk_bf16_f32 v34, v34, v35
	v_pk_mul_f32 v[36:37], v[36:37], v[40:41]
	s_nop 0
	v_pk_mul_f32 v[36:37], v[38:39], v[36:37]
	s_waitcnt vmcnt(14)
; __device__ __forceinline__ unsigned pk2(float lo, float hi) { f32x2 v = {lo, hi}; bf16x2_t b = __builtin_convertvector(v, bf16x2_t); return __builtin_bit_cast(unsigned, b); }
; __device__ __forceinline__ float silu_f(float z) { return z * __builtin_amdgcn_rcpf(1.0f + __expf(-z)); }
; template <int MODE>
; __device__ __forceinline__ void attn_unit(LAS unsigned char* lds, const bf16_t* __restrict__ qkvz, bf16_t* __restrict__ A2, const int b, const int hd, const int qb, const AttnX& X, const int tid) {
;     ...
;         for (int d = 0; d < NDT; ++d)
; #pragma unroll
;             for (int i4 = 0; i4 < 4; ++i4) { const int dd = 32 * d + 8 * i4 + 4 * hh_e; const u32x2 z2 = zz[d * 4 + i4];
;                 u32x2 w;
;                 w.x = pk2(O[d][4 * i4 + 0] * inv * silu_f(bflo(z2.x)), O[d][4 * i4 + 1] * inv * silu_f(bfhi(z2.x)));
;                 w.y = pk2(O[d][4 * i4 + 2] * inv * silu_f(bflo(z2.y)), O[d][4 * i4 + 3] * inv * silu_f(bfhi(z2.y)));
;                 *(u32x2*)(A2 + trow * DM + hd * C::DV + dd) = w; }
	v_lshlrev_b32_e32 v38, 16, v83
	v_cvt_pk_bf16_f32 v35, v36, v37
	global_store_dwordx2 v[66:67], v[34:35], off offset:112
	v_lshlrev_b32_e32 v34, 16, v82
	v_mul_f32_e32 v35, 0xbfb8aa3b, v34
	v_exp_f32_e32 v36, v35
	v_and_b32_e32 v35, 0xffff0000, v82
	v_mul_f32_e32 v37, 0xbfb8aa3b, v35
	v_exp_f32_e32 v37, v37
	v_and_b32_e32 v39, 0xffff0000, v83
	v_add_f32_e32 v36, 1.0, v36
	v_mul_f32_e32 v40, 0xbfb8aa3b, v38
	v_add_f32_e32 v37, 1.0, v37
	v_mul_f32_e32 v41, 0xbfb8aa3b, v39
	v_rcp_f32_e32 v36, v36
	v_rcp_f32_e32 v37, v37
	v_exp_f32_e32 v40, v40
	v_exp_f32_e32 v41, v41
	v_pk_mul_f32 v[34:35], v[36:37], v[34:35]
	v_add_f32_e32 v36, 1.0, v40
	v_add_f32_e32 v37, 1.0, v41
	v_rcp_f32_e32 v36, v36
	v_rcp_f32_e32 v37, v37
	v_pk_mul_f32 v[18:19], v[18:19], v[34:35]
	v_pk_mul_f32 v[34:35], v[36:37], v[38:39]
	s_nop 0
	v_pk_mul_f32 v[20:21], v[20:21], v[34:35]
	v_cvt_pk_bf16_f32 v18, v18, v19
	v_cvt_pk_bf16_f32 v19, v20, v21
	global_store_dwordx2 v[66:67], v[18:19], off offset:128
	s_waitcnt vmcnt(15)
	v_lshlrev_b32_e32 v18, 16, v80
	v_mul_f32_e32 v19, 0xbfb8aa3b, v18
	v_exp_f32_e32 v20, v19
	v_and_b32_e32 v19, 0xffff0000, v80
	v_mul_f32_e32 v21, 0xbfb8aa3b, v19
	v_exp_f32_e32 v21, v21
	v_lshlrev_b32_e32 v34, 16, v81
	v_and_b32_e32 v35, 0xffff0000, v81
	v_add_f32_e32 v20, 1.0, v20
	v_add_f32_e32 v21, 1.0, v21
	v_mul_f32_e32 v36, 0xbfb8aa3b, v34
	v_mul_f32_e32 v37, 0xbfb8aa3b, v35
	v_rcp_f32_e32 v20, v20
	v_rcp_f32_e32 v21, v21
	v_exp_f32_e32 v36, v36
	v_exp_f32_e32 v37, v37
	v_pk_mul_f32 v[18:19], v[20:21], v[18:19]
	v_add_f32_e32 v20, 1.0, v36
	v_add_f32_e32 v21, 1.0, v37
	v_rcp_f32_e32 v20, v20
	v_rcp_f32_e32 v21, v21
	v_pk_mul_f32 v[18:19], v[22:23], v[18:19]
	v_pk_mul_f32 v[22:23], v[24:25], v[0:1] op_sel_hi:[1,0]
	v_cvt_pk_bf16_f32 v18, v18, v19
	v_pk_mul_f32 v[20:21], v[20:21], v[34:35]
	s_waitcnt vmcnt(14)
	v_lshlrev_b32_e32 v24, 16, v79
	v_pk_mul_f32 v[20:21], v[22:23], v[20:21]
	v_and_b32_e32 v25, 0xffff0000, v79
	v_cvt_pk_bf16_f32 v19, v20, v21
	global_store_dwordx2 v[66:67], v[18:19], off offset:144
	v_lshlrev_b32_e32 v18, 16, v78
	v_mul_f32_e32 v19, 0xbfb8aa3b, v18
	v_exp_f32_e32 v20, v19
	v_and_b32_e32 v19, 0xffff0000, v78
	v_mul_f32_e32 v21, 0xbfb8aa3b, v19
	v_exp_f32_e32 v21, v21
	v_add_f32_e32 v20, 1.0, v20
	v_pk_mul_f32 v[22:23], v[26:27], v[0:1] op_sel_hi:[1,0]
	v_mul_f32_e32 v26, 0xbfb8aa3b, v24
	v_add_f32_e32 v21, 1.0, v21
	v_mul_f32_e32 v27, 0xbfb8aa3b, v25
	v_rcp_f32_e32 v20, v20
	v_rcp_f32_e32 v21, v21
	v_exp_f32_e32 v26, v26
	v_exp_f32_e32 v27, v27
	v_pk_mul_f32 v[18:19], v[20:21], v[18:19]
	v_add_f32_e32 v20, 1.0, v26
	v_add_f32_e32 v21, 1.0, v27
	v_rcp_f32_e32 v20, v20
	v_rcp_f32_e32 v21, v21
	v_pk_mul_f32 v[18:19], v[22:23], v[18:19]
	v_pk_mul_f32 v[22:23], v[28:29], v[0:1] op_sel_hi:[1,0]
	v_cvt_pk_bf16_f32 v18, v18, v19
	v_pk_mul_f32 v[20:21], v[20:21], v[24:25]
	s_waitcnt vmcnt(14)
	v_lshlrev_b32_e32 v24, 16, v77
	v_pk_mul_f32 v[20:21], v[22:23], v[20:21]
	v_and_b32_e32 v25, 0xffff0000, v77
	v_cvt_pk_bf16_f32 v19, v20, v21
	global_store_dwordx2 v[66:67], v[18:19], off offset:160
	v_lshlrev_b32_e32 v18, 16, v76
	v_mul_f32_e32 v19, 0xbfb8aa3b, v18
	v_exp_f32_e32 v20, v19
	v_and_b32_e32 v19, 0xffff0000, v76
	v_mul_f32_e32 v21, 0xbfb8aa3b, v19
	v_exp_f32_e32 v21, v21
	v_add_f32_e32 v20, 1.0, v20
	v_mul_f32_e32 v26, 0xbfb8aa3b, v24
	v_mul_f32_e32 v27, 0xbfb8aa3b, v25
	v_add_f32_e32 v21, 1.0, v21
	v_rcp_f32_e32 v20, v20
	v_rcp_f32_e32 v21, v21
	v_exp_f32_e32 v26, v26
	v_exp_f32_e32 v27, v27
	v_pk_mul_f32 v[22:23], v[30:31], v[0:1] op_sel_hi:[1,0]
	v_pk_mul_f32 v[18:19], v[20:21], v[18:19]
	v_add_f32_e32 v20, 1.0, v26
	v_add_f32_e32 v21, 1.0, v27
	v_rcp_f32_e32 v20, v20
	v_rcp_f32_e32 v21, v21
	v_pk_mul_f32 v[18:19], v[22:23], v[18:19]
	v_pk_mul_f32 v[22:23], v[32:33], v[0:1] op_sel_hi:[1,0]
	v_cvt_pk_bf16_f32 v18, v18, v19
	v_pk_mul_f32 v[20:21], v[20:21], v[24:25]
	s_nop 0
	v_pk_mul_f32 v[20:21], v[22:23], v[20:21]
	s_waitcnt vmcnt(14)
; __device__ __forceinline__ unsigned pk2(float lo, float hi) { f32x2 v = {lo, hi}; bf16x2_t b = __builtin_convertvector(v, bf16x2_t); return __builtin_bit_cast(unsigned, b); }
; __device__ __forceinline__ float silu_f(float z) { return z * __builtin_amdgcn_rcpf(1.0f + __expf(-z)); }
; template <int MODE>
; __device__ __forceinline__ void attn_unit(LAS unsigned char* lds, const bf16_t* __restrict__ qkvz, bf16_t* __restrict__ A2, const int b, const int hd, const int qb, const AttnX& X, const int tid) {
;     ...
;         for (int d = 0; d < NDT; ++d)
; #pragma unroll
;             for (int i4 = 0; i4 < 4; ++i4) { const int dd = 32 * d + 8 * i4 + 4 * hh_e; const u32x2 z2 = zz[d * 4 + i4];
;                 u32x2 w;
;                 w.x = pk2(O[d][4 * i4 + 0] * inv * silu_f(bflo(z2.x)), O[d][4 * i4 + 1] * inv * silu_f(bfhi(z2.x)));
;                 w.y = pk2(O[d][4 * i4 + 2] * inv * silu_f(bflo(z2.y)), O[d][4 * i4 + 3] * inv * silu_f(bfhi(z2.y)));
;                 *(u32x2*)(A2 + trow * DM + hd * C::DV + dd) = w; }
;     ...
;     __syncthreads();
	v_lshlrev_b32_e32 v22, 16, v75
	v_cvt_pk_bf16_f32 v19, v20, v21
	global_store_dwordx2 v[66:67], v[18:19], off offset:176
	v_lshlrev_b32_e32 v18, 16, v74
	v_mul_f32_e32 v19, 0xbfb8aa3b, v18
	v_exp_f32_e32 v20, v19
	v_and_b32_e32 v19, 0xffff0000, v74
	v_mul_f32_e32 v21, 0xbfb8aa3b, v19
	v_exp_f32_e32 v21, v21
	v_and_b32_e32 v23, 0xffff0000, v75
	v_add_f32_e32 v20, 1.0, v20
	v_mul_f32_e32 v24, 0xbfb8aa3b, v22
	v_add_f32_e32 v21, 1.0, v21
	v_mul_f32_e32 v25, 0xbfb8aa3b, v23
	v_rcp_f32_e32 v20, v20
	v_rcp_f32_e32 v21, v21
	v_exp_f32_e32 v24, v24
	v_exp_f32_e32 v25, v25
	v_pk_mul_f32 v[18:19], v[20:21], v[18:19]
	v_add_f32_e32 v20, 1.0, v24
	v_add_f32_e32 v21, 1.0, v25
	v_rcp_f32_e32 v20, v20
	v_rcp_f32_e32 v21, v21
	v_pk_mul_f32 v[2:3], v[2:3], v[18:19]
	v_pk_mul_f32 v[18:19], v[20:21], v[22:23]
	s_nop 0
	v_pk_mul_f32 v[4:5], v[4:5], v[18:19]
	v_cvt_pk_bf16_f32 v2, v2, v3
	v_cvt_pk_bf16_f32 v3, v4, v5
	global_store_dwordx2 v[66:67], v[2:3], off offset:192
	s_waitcnt vmcnt(15)
	v_lshlrev_b32_e32 v2, 16, v72
	v_mul_f32_e32 v3, 0xbfb8aa3b, v2
	v_exp_f32_e32 v4, v3
	v_and_b32_e32 v3, 0xffff0000, v72
	v_mul_f32_e32 v5, 0xbfb8aa3b, v3
	v_exp_f32_e32 v5, v5
	v_lshlrev_b32_e32 v18, 16, v73
	v_and_b32_e32 v19, 0xffff0000, v73
	v_add_f32_e32 v4, 1.0, v4
	v_add_f32_e32 v5, 1.0, v5
	v_mul_f32_e32 v20, 0xbfb8aa3b, v18
	v_mul_f32_e32 v21, 0xbfb8aa3b, v19
	v_rcp_f32_e32 v4, v4
	v_rcp_f32_e32 v5, v5
	v_exp_f32_e32 v20, v20
	v_exp_f32_e32 v21, v21
	v_pk_mul_f32 v[2:3], v[4:5], v[2:3]
	v_add_f32_e32 v4, 1.0, v20
	v_add_f32_e32 v5, 1.0, v21
	v_rcp_f32_e32 v4, v4
	v_rcp_f32_e32 v5, v5
	v_pk_mul_f32 v[2:3], v[6:7], v[2:3]
	v_pk_mul_f32 v[6:7], v[8:9], v[0:1] op_sel_hi:[1,0]
	v_cvt_pk_bf16_f32 v2, v2, v3
	v_pk_mul_f32 v[4:5], v[4:5], v[18:19]
	s_waitcnt vmcnt(14)
	v_lshlrev_b32_e32 v8, 16, v71
	v_pk_mul_f32 v[4:5], v[6:7], v[4:5]
	v_and_b32_e32 v9, 0xffff0000, v71
	v_cvt_pk_bf16_f32 v3, v4, v5
	global_store_dwordx2 v[66:67], v[2:3], off offset:208
	v_lshlrev_b32_e32 v2, 16, v70
	v_mul_f32_e32 v3, 0xbfb8aa3b, v2
	v_exp_f32_e32 v4, v3
	v_and_b32_e32 v3, 0xffff0000, v70
	v_mul_f32_e32 v5, 0xbfb8aa3b, v3
	v_exp_f32_e32 v5, v5
	v_add_f32_e32 v4, 1.0, v4
	v_pk_mul_f32 v[6:7], v[10:11], v[0:1] op_sel_hi:[1,0]
	v_mul_f32_e32 v10, 0xbfb8aa3b, v8
	v_add_f32_e32 v5, 1.0, v5
	v_mul_f32_e32 v11, 0xbfb8aa3b, v9
	v_rcp_f32_e32 v4, v4
	v_rcp_f32_e32 v5, v5
	v_exp_f32_e32 v10, v10
	v_exp_f32_e32 v11, v11
	v_pk_mul_f32 v[2:3], v[4:5], v[2:3]
	v_add_f32_e32 v4, 1.0, v10
	v_add_f32_e32 v5, 1.0, v11
	v_rcp_f32_e32 v4, v4
	v_rcp_f32_e32 v5, v5
	v_pk_mul_f32 v[2:3], v[6:7], v[2:3]
	v_pk_mul_f32 v[6:7], v[12:13], v[0:1] op_sel_hi:[1,0]
	v_cvt_pk_bf16_f32 v2, v2, v3
	v_pk_mul_f32 v[4:5], v[4:5], v[8:9]
	s_waitcnt vmcnt(14)
	v_lshlrev_b32_e32 v8, 16, v69
	v_pk_mul_f32 v[4:5], v[6:7], v[4:5]
	v_and_b32_e32 v9, 0xffff0000, v69
	v_cvt_pk_bf16_f32 v3, v4, v5
	global_store_dwordx2 v[66:67], v[2:3], off offset:224
	v_lshlrev_b32_e32 v2, 16, v68
	v_mul_f32_e32 v3, 0xbfb8aa3b, v2
	v_exp_f32_e32 v4, v3
	v_and_b32_e32 v3, 0xffff0000, v68
	v_mul_f32_e32 v5, 0xbfb8aa3b, v3
	v_exp_f32_e32 v5, v5
	v_add_f32_e32 v4, 1.0, v4
	v_mul_f32_e32 v10, 0xbfb8aa3b, v8
	v_mul_f32_e32 v11, 0xbfb8aa3b, v9
	v_add_f32_e32 v5, 1.0, v5
	v_rcp_f32_e32 v4, v4
	v_rcp_f32_e32 v5, v5
	v_exp_f32_e32 v10, v10
	v_exp_f32_e32 v11, v11
	v_pk_mul_f32 v[6:7], v[14:15], v[0:1] op_sel_hi:[1,0]
	v_pk_mul_f32 v[2:3], v[4:5], v[2:3]
	v_add_f32_e32 v4, 1.0, v10
	v_add_f32_e32 v5, 1.0, v11
	v_rcp_f32_e32 v4, v4
	v_rcp_f32_e32 v5, v5
	v_pk_mul_f32 v[2:3], v[6:7], v[2:3]
	v_pk_mul_f32 v[6:7], v[16:17], v[0:1] op_sel_hi:[1,0]
	v_cvt_pk_bf16_f32 v2, v2, v3
	v_pk_mul_f32 v[4:5], v[4:5], v[8:9]
	s_nop 0
	v_pk_mul_f32 v[4:5], v[6:7], v[4:5]
	s_nop 0
	v_cvt_pk_bf16_f32 v3, v4, v5
	global_store_dwordx2 v[66:67], v[2:3], off offset:240
	s_waitcnt lgkmcnt(0)
	s_barrier
	v_cmp_eq_u32_e32 vcc, 0, v212
	s_and_saveexec_b64 s[2:3], vcc
	s_cbranch_execz .Lfox_nofetch
	s_waitcnt vmcnt(0)
	v_mov_b32_e32 v3, 0x23ff8
	ds_write_b32 v3, v250
